# meta rows K|V|U projection on the matrix cores (one 16x16 tile per workgroup, K split over its waves, LDS reduce) instead of per-column VALU dots + ds_bpermute butterflies
# speedup vs baseline: 1.0082x; 1.0030x over previous
; __device__ __forceinline__ unsigned cvt_pk(float lo, float hi) { unsigned r; asm volatile("v_cvt_pk_bf16_f32 %0, %1, %2" : "=v"(r) : "v"(lo), "v"(hi)); return r; }
; __device__ __forceinline__ float bf_lo(unsigned w) { return __uint_as_float(w << 16); }
; __device__ __forceinline__ float bf_hi(unsigned w) { return __uint_as_float(w & 0xffff0000u); }
; __device__ __forceinline__ void meta_proj(const Args& a, int wave, int lane) {
;     unsigned char* ws = a.ws;
;     const bf16* XB = (const bf16*)(ws + WS_XB); const bf16* W1t = (const bf16*)(ws + WS_W1); const float* rstdx = (const float*)(ws + WS_RSTDX);
;     for (int gw = blockIdx.x * NWAVES + wave; gw < 1536; gw += gridDim.x * NWAVES) {
;     const int n = 1024 + gw;
;     float wf[16];
;     { const u32x4 w0 = *(const u32x4*)(W1t + (size_t)n * DM + lane * 8), w1 = *(const u32x4*)(W1t + (size_t)n * DM + 512 + lane * 8);
;       const unsigned ww[8] = {w0.x, w0.y, w0.z, w0.w, w1.x, w1.y, w1.z, w1.w};
; #pragma unroll
;       for (int e = 0; e < 8; ++e) { wf[2 * e] = bf_lo(ww[e]); wf[2 * e + 1] = bf_hi(ww[e]); } }
;     float mine = 0.f;
; #pragma unroll
;     for (int r = 0; r < 16; ++r) {
;         const u32x4 x0 = *(const u32x4*)(XB + (size_t)(META_ROW + r) * DM + lane * 8), x1 = *(const u32x4*)(XB + (size_t)(META_ROW + r) * DM + 512 + lane * 8);
;         const unsigned xx[8] = {x0.x, x0.y, x0.z, x0.w, x1.x, x1.y, x1.z, x1.w};
;         float s = 0.f;
; #pragma unroll
;         for (int e = 0; e < 8; ++e) s += bf_lo(xx[e]) * wf[2 * e] + bf_hi(xx[e]) * wf[2 * e + 1];
;         s = wave_sum(s);
;         if (lane == r) mine = s;
;     }
;     if (lane < 16) {
;         const unsigned short o = (unsigned short)(cvt_pk(mine * rstdx[META_ROW + lane], 0.f) & 0xffffu);
;         const size_t row = META_ROW + lane;
;         if (n < 1280) ((bf16*)(ws + WS_K))[row * KVW + (n - 1024)] = o;
;         else if (n < 1536) ((bf16*)(ws + WS_V))[row * KVW + (n - 1280)] = o;
;         else ((bf16*)(ws + WS_U))[row * DM + (n - 1536)] = o;
;     }
;     }
; }
.LBB0_157:
	s_or_b64 exec, exec, s[0:1]
	s_add_u32 s42, s58, 0x200000
	s_addc_u32 s43, s59, 0
	s_cmpk_gt_i32 s38, 0x5ff
	s_waitcnt lgkmcnt(0)
	s_barrier
	s_cmpk_gt_i32 s2, 0x5f
	s_cbranch_scc1 .LBB0_169
	v_and_b32_e32 v0, 63, v224
	v_and_b32_e32 v1, 15, v0
	v_lshrrev_b32_e32 v2, 4, v0
	s_lshl_b32 s4, s33, 8
	v_lshl_add_u32 v4, v2, 4, s4
	v_lshl_add_u32 v5, v1, 11, v4
	s_add_u32 s6, s58, 0x6c00000
	s_addc_u32 s7, s59, 0
	s_lshl_b32 s8, s2, 15
	s_add_u32 s8, s8, 0x200000
	s_add_u32 s8, s42, s8
	s_addc_u32 s9, s43, 0
	global_load_dwordx4 v[8:11], v5, s[6:7]
	global_load_dwordx4 v[12:15], v5, s[6:7] offset:64
	global_load_dwordx4 v[16:19], v5, s[6:7] offset:128
	global_load_dwordx4 v[20:23], v5, s[6:7] offset:192
	global_load_dwordx4 v[24:27], v5, s[8:9]
	global_load_dwordx4 v[28:31], v5, s[8:9] offset:64
	global_load_dwordx4 v[32:35], v5, s[8:9] offset:128
	global_load_dwordx4 v[36:39], v5, s[8:9] offset:192
	v_lshlrev_b32_e32 v6, 4, v2
	v_add_u32_e32 v6, 0x20000, v6
	global_load_dwordx4 v[40:43], v6, s[58:59]
	s_lshl_b32 s5, s33, 10
	v_lshl_add_u32 v7, v0, 4, s5
	v_add_u32_e32 v7, 0x20000, v7
	s_waitcnt vmcnt(1)
	v_mfma_f32_16x16x32_bf16 v[44:47], v[8:11], v[24:27], 0
	v_mfma_f32_16x16x32_bf16 v[44:47], v[12:15], v[28:31], v[44:47]
	v_mfma_f32_16x16x32_bf16 v[44:47], v[16:19], v[32:35], v[44:47]
	v_mfma_f32_16x16x32_bf16 v[44:47], v[20:23], v[36:39], v[44:47]
	s_nop 11
	s_nop 3
	ds_write_b128 v7, v[44:47]
	s_waitcnt lgkmcnt(0)
	s_barrier
	s_cmp_lg_u32 s33, 0
	s_cbranch_scc1 .LBB0_169
	v_lshlrev_b32_e32 v7, 4, v0
	v_add_u32_e32 v7, 0x20000, v7
	ds_read_b128 v[48:51], v7
	ds_read_b128 v[52:55], v7 offset:1024
	ds_read_b128 v[56:59], v7 offset:2048
	ds_read_b128 v[60:63], v7 offset:3072
	ds_read_b128 v[64:67], v7 offset:4096
	ds_read_b128 v[68:71], v7 offset:5120
	ds_read_b128 v[72:75], v7 offset:6144
	ds_read_b128 v[76:79], v7 offset:7168
	s_mov_b32 s10, 0xaf00000
	s_mov_b32 s11, 9
	s_mov_b32 s12, s2
	s_cmp_lt_u32 s2, 16
	s_cbranch_scc1 .Lmeta_reg
	s_mov_b32 s10, 0xc000000
	s_sub_u32 s12, s2, 16
	s_cmp_lt_u32 s2, 32
	s_cbranch_scc1 .Lmeta_reg
	s_mov_b32 s10, 0xd100000
	s_mov_b32 s11, 11
	s_sub_u32 s12, s2, 32
.Lmeta_reg:
	s_add_u32 s14, s58, s10
	s_addc_u32 s15, s59, 0
	s_lshl_b32 s12, s12, 5
	s_lshl_b32 s13, 1, s11
	v_lshlrev_b32_e32 v4, 2, v2
	v_add_u32_e32 v4, 0x8000, v4
	v_lshlrev_b32_e32 v4, s11, v4
	v_lshl_add_u32 v4, v1, 1, v4
	v_add_u32_e32 v4, s12, v4
	s_waitcnt lgkmcnt(0)
	v_pk_add_f32 v[48:49], v[48:49], v[52:53]
	v_pk_add_f32 v[50:51], v[50:51], v[54:55]
	v_pk_add_f32 v[48:49], v[48:49], v[56:57]
	v_pk_add_f32 v[50:51], v[50:51], v[58:59]
	v_pk_add_f32 v[48:49], v[48:49], v[60:61]
	v_pk_add_f32 v[50:51], v[50:51], v[62:63]
	v_pk_add_f32 v[48:49], v[48:49], v[64:65]
	v_pk_add_f32 v[50:51], v[50:51], v[66:67]
	v_pk_add_f32 v[48:49], v[48:49], v[68:69]
	v_pk_add_f32 v[50:51], v[50:51], v[70:71]
	v_pk_add_f32 v[48:49], v[48:49], v[72:73]
	v_pk_add_f32 v[50:51], v[50:51], v[74:75]
	v_pk_add_f32 v[48:49], v[48:49], v[76:77]
	v_pk_add_f32 v[50:51], v[50:51], v[78:79]
	s_waitcnt vmcnt(0)
	v_pk_mul_f32 v[48:49], v[48:49], v[40:41]
	v_pk_mul_f32 v[50:51], v[50:51], v[42:43]
	v_mov_b32_e32 v5, 0
	s_nop 0
	v_cvt_pk_bf16_f32 v52, v48, v5
	v_cvt_pk_bf16_f32 v53, v49, v5
	v_cvt_pk_bf16_f32 v54, v50, v5
	v_cvt_pk_bf16_f32 v55, v51, v5
	global_store_short v4, v52, s[14:15]
	v_add_u32_e32 v4, s13, v4
	global_store_short v4, v53, s[14:15]
	v_add_u32_e32 v4, s13, v4
	global_store_short v4, v54, s[14:15]
	v_add_u32_e32 v4, s13, v4
	global_store_short v4, v55, s[14:15]
	s_branch .LBB0_169
